# combo + GEMM prologues: K-loop setup and accumulator zero-init moved in front of the prologue barrier
# speedup vs baseline: 1.0007x; 1.0007x over previous
.LBB0_83:
	s_cmp_lt_i32 s3, 1
	v_lshrrev_b32_e32 v2, 4, v15
	v_bfe_u32 v4, v15, 4, 2
	v_and_b32_e32 v5, 15, v15
	v_bitop3_b32 v8, v2, v5, 3 bitop3:0x6c
	v_or_b32_e32 v2, 4, v4
	v_ashrrev_i32_e32 v7, 1, v15
	v_lshlrev_b32_e32 v9, 8, v2
	v_add_u32_e32 v2, v17, v14
	v_and_b32_e32 v3, 0xc0, v15
	v_lshlrev_b32_e32 v6, 8, v4
	v_and_b32_e32 v7, 0xffffff80, v7
	v_bitop3_b32 v4, v4, v5, 4 bitop3:0x36
	v_add_lshl_u32 v231, v2, v16, 12
	v_mov_b32_e32 v2, 0
	s_mov_b32 s45, 0
	v_lshlrev_b32_e32 v232, 4, v6
	v_lshlrev_b32_e32 v233, 4, v7
	v_lshlrev_b32_e32 v234, 4, v9
	v_lshlrev_b32_e32 v235, 4, v3
	v_lshlrev_b32_e32 v236, 4, v8
	v_lshlrev_b32_e32 v237, 4, v4
	s_mov_b32 s46, 0
	v_mov_b32_e32 v3, v2
	v_mov_b32_e32 v4, v2
	v_mov_b32_e32 v5, v2
	v_mov_b32_e32 v6, v2
	v_mov_b32_e32 v7, v2
	v_mov_b32_e32 v8, v2
	v_mov_b32_e32 v9, v2
	v_mov_b32_e32 v10, v2
	v_mov_b32_e32 v11, v2
	v_mov_b32_e32 v12, v2
	v_mov_b32_e32 v13, v2
	v_mov_b32_e32 v14, v2
	v_mov_b32_e32 v15, v2
	v_mov_b32_e32 v16, v2
	v_mov_b32_e32 v17, v2
	v_mov_b32_e32 v18, v2
	v_mov_b32_e32 v19, v2
	v_mov_b32_e32 v20, v2
	v_mov_b32_e32 v21, v2
	v_mov_b32_e32 v22, v2
	v_mov_b32_e32 v23, v2
	v_mov_b32_e32 v24, v2
	v_mov_b32_e32 v25, v2
	v_mov_b32_e32 v26, v2
	v_mov_b32_e32 v27, v2
	v_mov_b32_e32 v28, v2
	v_mov_b32_e32 v29, v2
	v_mov_b32_e32 v30, v2
	v_mov_b32_e32 v31, v2
	v_mov_b32_e32 v32, v2
	v_mov_b32_e32 v33, v2
	v_mov_b32_e32 v36, v2
	v_mov_b32_e32 v37, v2
	v_mov_b32_e32 v38, v2
	v_mov_b32_e32 v39, v2
	v_mov_b32_e32 v40, v2
	v_mov_b32_e32 v41, v2
	v_mov_b32_e32 v42, v2
	v_mov_b32_e32 v43, v2
	v_mov_b32_e32 v44, v2
	v_mov_b32_e32 v45, v2
	v_mov_b32_e32 v46, v2
	v_mov_b32_e32 v47, v2
	v_mov_b32_e32 v48, v2
	v_mov_b32_e32 v49, v2
	v_mov_b32_e32 v50, v2
	v_mov_b32_e32 v51, v2
	v_mov_b32_e32 v52, v2
	v_mov_b32_e32 v53, v2
	v_mov_b32_e32 v54, v2
	v_mov_b32_e32 v55, v2
	v_mov_b32_e32 v56, v2
	v_mov_b32_e32 v57, v2
	v_mov_b32_e32 v58, v2
	v_mov_b32_e32 v59, v2
	v_mov_b32_e32 v60, v2
	v_mov_b32_e32 v61, v2
	v_mov_b32_e32 v62, v2
	v_mov_b32_e32 v63, v2
	v_mov_b32_e32 v64, v2
	v_mov_b32_e32 v65, v2
	v_mov_b32_e32 v66, v2
	v_mov_b32_e32 v67, v2
	v_mov_b32_e32 v68, v2
	v_mov_b32_e32 v69, v2
	v_mov_b32_e32 v70, v2
	v_mov_b32_e32 v71, v2
	v_mov_b32_e32 v72, v2
	v_mov_b32_e32 v73, v2
	v_mov_b32_e32 v74, v2
	v_mov_b32_e32 v75, v2
	v_mov_b32_e32 v76, v2
	v_mov_b32_e32 v77, v2
	v_mov_b32_e32 v78, v2
	v_mov_b32_e32 v79, v2
	v_mov_b32_e32 v80, v2
	v_mov_b32_e32 v81, v2
	v_mov_b32_e32 v82, v2
	v_mov_b32_e32 v83, v2
	v_mov_b32_e32 v84, v2
	v_mov_b32_e32 v85, v2
	v_mov_b32_e32 v86, v2
	v_mov_b32_e32 v87, v2
	v_mov_b32_e32 v88, v2
	v_mov_b32_e32 v89, v2
	v_mov_b32_e32 v90, v2
	v_mov_b32_e32 v91, v2
	v_mov_b32_e32 v92, v2
	v_mov_b32_e32 v93, v2
	v_mov_b32_e32 v94, v2
	v_mov_b32_e32 v95, v2
	v_mov_b32_e32 v96, v2
	v_mov_b32_e32 v97, v2
	v_mov_b32_e32 v98, v2
	v_mov_b32_e32 v99, v2
	v_mov_b32_e32 v100, v2
	v_mov_b32_e32 v101, v2
	v_mov_b32_e32 v102, v2
	v_mov_b32_e32 v103, v2
	v_mov_b32_e32 v104, v2
	v_mov_b32_e32 v105, v2
	v_mov_b32_e32 v106, v2
	v_mov_b32_e32 v107, v2
	v_mov_b32_e32 v108, v2
	v_mov_b32_e32 v109, v2
	v_mov_b32_e32 v110, v2
	v_mov_b32_e32 v111, v2
	v_mov_b32_e32 v112, v2
	v_mov_b32_e32 v113, v2
	v_mov_b32_e32 v114, v2
	v_mov_b32_e32 v115, v2
	v_mov_b32_e32 v116, v2
	v_mov_b32_e32 v117, v2
	v_mov_b32_e32 v118, v2
	v_mov_b32_e32 v119, v2
	v_mov_b32_e32 v120, v2
	v_mov_b32_e32 v121, v2
	v_mov_b32_e32 v122, v2
	v_mov_b32_e32 v123, v2
	v_mov_b32_e32 v128, v2
	v_mov_b32_e32 v129, v2
	v_mov_b32_e32 v130, v2
	v_mov_b32_e32 v131, v2
	v_mov_b32_e32 v148, v2
	v_mov_b32_e32 v149, v2
	v_mov_b32_e32 v150, v2
	v_mov_b32_e32 v151, v2
	s_waitcnt lgkmcnt(0)
	s_barrier
	s_cbranch_scc1 .LBB0_90

.LBB0_134:
	s_cmp_lt_i32 s3, 1
	v_lshrrev_b32_e32 v2, 4, v15
	v_bfe_u32 v4, v15, 4, 2
	v_and_b32_e32 v5, 15, v15
	v_bitop3_b32 v8, v2, v5, 3 bitop3:0x6c
	v_or_b32_e32 v2, 4, v4
	v_ashrrev_i32_e32 v7, 1, v15
	v_lshlrev_b32_e32 v9, 8, v2
	v_add_u32_e32 v2, v17, v14
	v_and_b32_e32 v3, 0xc0, v15
	v_lshlrev_b32_e32 v6, 8, v4
	v_and_b32_e32 v7, 0xffffff80, v7
	v_bitop3_b32 v4, v4, v5, 4 bitop3:0x36
	v_add_lshl_u32 v231, v2, v16, 10
	v_mov_b32_e32 v2, 0
	s_mov_b32 s23, 0
	v_lshlrev_b32_e32 v232, 4, v6
	v_lshlrev_b32_e32 v233, 4, v7
	v_lshlrev_b32_e32 v234, 4, v9
	v_lshlrev_b32_e32 v235, 4, v3
	v_lshlrev_b32_e32 v236, 4, v8
	v_lshlrev_b32_e32 v237, 4, v4
	s_mov_b32 s42, 0
	v_mov_b32_e32 v3, v2
	v_mov_b32_e32 v4, v2
	v_mov_b32_e32 v5, v2
	v_mov_b32_e32 v6, v2
	v_mov_b32_e32 v7, v2
	v_mov_b32_e32 v8, v2
	v_mov_b32_e32 v9, v2
	v_mov_b32_e32 v10, v2
	v_mov_b32_e32 v11, v2
	v_mov_b32_e32 v12, v2
	v_mov_b32_e32 v13, v2
	v_mov_b32_e32 v14, v2
	v_mov_b32_e32 v15, v2
	v_mov_b32_e32 v16, v2
	v_mov_b32_e32 v17, v2
	v_mov_b32_e32 v18, v2
	v_mov_b32_e32 v19, v2
	v_mov_b32_e32 v20, v2
	v_mov_b32_e32 v21, v2
	v_mov_b32_e32 v22, v2
	v_mov_b32_e32 v23, v2
	v_mov_b32_e32 v24, v2
	v_mov_b32_e32 v25, v2
	v_mov_b32_e32 v26, v2
	v_mov_b32_e32 v27, v2
	v_mov_b32_e32 v28, v2
	v_mov_b32_e32 v29, v2
	v_mov_b32_e32 v30, v2
	v_mov_b32_e32 v31, v2
	v_mov_b32_e32 v32, v2
	v_mov_b32_e32 v33, v2
	v_mov_b32_e32 v36, v2
	v_mov_b32_e32 v37, v2
	v_mov_b32_e32 v38, v2
	v_mov_b32_e32 v39, v2
	v_mov_b32_e32 v40, v2
	v_mov_b32_e32 v41, v2
	v_mov_b32_e32 v42, v2
	v_mov_b32_e32 v43, v2
	v_mov_b32_e32 v44, v2
	v_mov_b32_e32 v45, v2
	v_mov_b32_e32 v46, v2
	v_mov_b32_e32 v47, v2
	v_mov_b32_e32 v48, v2
	v_mov_b32_e32 v49, v2
	v_mov_b32_e32 v50, v2
	v_mov_b32_e32 v51, v2
	v_mov_b32_e32 v52, v2
	v_mov_b32_e32 v53, v2
	v_mov_b32_e32 v54, v2
	v_mov_b32_e32 v55, v2
	v_mov_b32_e32 v56, v2
	v_mov_b32_e32 v57, v2
	v_mov_b32_e32 v58, v2
	v_mov_b32_e32 v59, v2
	v_mov_b32_e32 v60, v2
	v_mov_b32_e32 v61, v2
	v_mov_b32_e32 v62, v2
	v_mov_b32_e32 v63, v2
	v_mov_b32_e32 v64, v2
	v_mov_b32_e32 v65, v2
	v_mov_b32_e32 v66, v2
	v_mov_b32_e32 v67, v2
	v_mov_b32_e32 v68, v2
	v_mov_b32_e32 v69, v2
	v_mov_b32_e32 v70, v2
	v_mov_b32_e32 v71, v2
	v_mov_b32_e32 v72, v2
	v_mov_b32_e32 v73, v2
	v_mov_b32_e32 v74, v2
	v_mov_b32_e32 v75, v2
	v_mov_b32_e32 v76, v2
	v_mov_b32_e32 v77, v2
	v_mov_b32_e32 v78, v2
	v_mov_b32_e32 v79, v2
	v_mov_b32_e32 v80, v2
	v_mov_b32_e32 v81, v2
	v_mov_b32_e32 v82, v2
	v_mov_b32_e32 v83, v2
	v_mov_b32_e32 v84, v2
	v_mov_b32_e32 v85, v2
	v_mov_b32_e32 v86, v2
	v_mov_b32_e32 v87, v2
	v_mov_b32_e32 v88, v2
	v_mov_b32_e32 v89, v2
	v_mov_b32_e32 v90, v2
	v_mov_b32_e32 v91, v2
	v_mov_b32_e32 v92, v2
	v_mov_b32_e32 v93, v2
	v_mov_b32_e32 v94, v2
	v_mov_b32_e32 v95, v2
	v_mov_b32_e32 v96, v2
	v_mov_b32_e32 v97, v2
	v_mov_b32_e32 v98, v2
	v_mov_b32_e32 v99, v2
	v_mov_b32_e32 v100, v2
	v_mov_b32_e32 v101, v2
	v_mov_b32_e32 v102, v2
	v_mov_b32_e32 v103, v2
	v_mov_b32_e32 v104, v2
	v_mov_b32_e32 v105, v2
	v_mov_b32_e32 v106, v2
	v_mov_b32_e32 v107, v2
	v_mov_b32_e32 v108, v2
	v_mov_b32_e32 v109, v2
	v_mov_b32_e32 v110, v2
	v_mov_b32_e32 v111, v2
	v_mov_b32_e32 v112, v2
	v_mov_b32_e32 v113, v2
	v_mov_b32_e32 v114, v2
	v_mov_b32_e32 v115, v2
	v_mov_b32_e32 v124, v2
	v_mov_b32_e32 v125, v2
	v_mov_b32_e32 v126, v2
	v_mov_b32_e32 v127, v2
	v_mov_b32_e32 v132, v2
	v_mov_b32_e32 v133, v2
	v_mov_b32_e32 v134, v2
	v_mov_b32_e32 v135, v2
	v_mov_b32_e32 v148, v2
	v_mov_b32_e32 v149, v2
	v_mov_b32_e32 v150, v2
	v_mov_b32_e32 v151, v2
	v_mov_b32_e32 v156, v2
	v_mov_b32_e32 v157, v2
	v_mov_b32_e32 v158, v2
	v_mov_b32_e32 v159, v2
	s_waitcnt lgkmcnt(0)
	s_barrier
	s_cbranch_scc1 .LBB0_141

.LBB0_192:
	s_cmp_lt_i32 s3, 1
	v_lshrrev_b32_e32 v2, 4, v15
	v_bfe_u32 v4, v15, 4, 2
	v_and_b32_e32 v5, 15, v15
	v_bitop3_b32 v8, v2, v5, 3 bitop3:0x6c
	v_or_b32_e32 v2, 4, v4
	v_ashrrev_i32_e32 v7, 1, v15
	v_lshlrev_b32_e32 v9, 8, v2
	v_add_u32_e32 v2, v17, v14
	v_and_b32_e32 v3, 0xc0, v15
	v_lshlrev_b32_e32 v6, 8, v4
	v_and_b32_e32 v7, 0xffffff80, v7
	v_bitop3_b32 v4, v4, v5, 4 bitop3:0x36
	v_add_lshl_u32 v231, v2, v16, 10
	v_mov_b32_e32 v2, 0
	s_mov_b32 s47, 0
	v_lshlrev_b32_e32 v232, 4, v6
	v_lshlrev_b32_e32 v233, 4, v7
	v_lshlrev_b32_e32 v234, 4, v9
	v_lshlrev_b32_e32 v235, 4, v3
	v_lshlrev_b32_e32 v236, 4, v8
	v_lshlrev_b32_e32 v237, 4, v4
	s_mov_b32 s48, 0
	v_mov_b32_e32 v3, v2
	v_mov_b32_e32 v4, v2
	v_mov_b32_e32 v5, v2
	v_mov_b32_e32 v6, v2
	v_mov_b32_e32 v7, v2
	v_mov_b32_e32 v8, v2
	v_mov_b32_e32 v9, v2
	v_mov_b32_e32 v10, v2
	v_mov_b32_e32 v11, v2
	v_mov_b32_e32 v12, v2
	v_mov_b32_e32 v13, v2
	v_mov_b32_e32 v14, v2
	v_mov_b32_e32 v15, v2
	v_mov_b32_e32 v16, v2
	v_mov_b32_e32 v17, v2
	v_mov_b32_e32 v18, v2
	v_mov_b32_e32 v19, v2
	v_mov_b32_e32 v20, v2
	v_mov_b32_e32 v21, v2
	v_mov_b32_e32 v22, v2
	v_mov_b32_e32 v23, v2
	v_mov_b32_e32 v24, v2
	v_mov_b32_e32 v25, v2
	v_mov_b32_e32 v26, v2
	v_mov_b32_e32 v27, v2
	v_mov_b32_e32 v28, v2
	v_mov_b32_e32 v29, v2
	v_mov_b32_e32 v30, v2
	v_mov_b32_e32 v31, v2
	v_mov_b32_e32 v32, v2
	v_mov_b32_e32 v33, v2
	v_mov_b32_e32 v36, v2
	v_mov_b32_e32 v37, v2
	v_mov_b32_e32 v38, v2
	v_mov_b32_e32 v39, v2
	v_mov_b32_e32 v40, v2
	v_mov_b32_e32 v41, v2
	v_mov_b32_e32 v42, v2
	v_mov_b32_e32 v43, v2
	v_mov_b32_e32 v44, v2
	v_mov_b32_e32 v45, v2
	v_mov_b32_e32 v46, v2
	v_mov_b32_e32 v47, v2
	v_mov_b32_e32 v48, v2
	v_mov_b32_e32 v49, v2
	v_mov_b32_e32 v50, v2
	v_mov_b32_e32 v51, v2
	v_mov_b32_e32 v52, v2
	v_mov_b32_e32 v53, v2
	v_mov_b32_e32 v54, v2
	v_mov_b32_e32 v55, v2
	v_mov_b32_e32 v56, v2
	v_mov_b32_e32 v57, v2
	v_mov_b32_e32 v58, v2
	v_mov_b32_e32 v59, v2
	v_mov_b32_e32 v60, v2
	v_mov_b32_e32 v61, v2
	v_mov_b32_e32 v62, v2
	v_mov_b32_e32 v63, v2
	v_mov_b32_e32 v64, v2
	v_mov_b32_e32 v65, v2
	v_mov_b32_e32 v66, v2
	v_mov_b32_e32 v67, v2
	v_mov_b32_e32 v68, v2
	v_mov_b32_e32 v69, v2
	v_mov_b32_e32 v70, v2
	v_mov_b32_e32 v71, v2
	v_mov_b32_e32 v72, v2
	v_mov_b32_e32 v73, v2
	v_mov_b32_e32 v74, v2
	v_mov_b32_e32 v75, v2
	v_mov_b32_e32 v76, v2
	v_mov_b32_e32 v77, v2
	v_mov_b32_e32 v78, v2
	v_mov_b32_e32 v79, v2
	v_mov_b32_e32 v80, v2
	v_mov_b32_e32 v81, v2
	v_mov_b32_e32 v82, v2
	v_mov_b32_e32 v83, v2
	v_mov_b32_e32 v84, v2
	v_mov_b32_e32 v85, v2
	v_mov_b32_e32 v86, v2
	v_mov_b32_e32 v87, v2
	v_mov_b32_e32 v88, v2
	v_mov_b32_e32 v89, v2
	v_mov_b32_e32 v90, v2
	v_mov_b32_e32 v91, v2
	v_mov_b32_e32 v92, v2
	v_mov_b32_e32 v93, v2
	v_mov_b32_e32 v94, v2
	v_mov_b32_e32 v95, v2
	v_mov_b32_e32 v96, v2
	v_mov_b32_e32 v97, v2
	v_mov_b32_e32 v98, v2
	v_mov_b32_e32 v99, v2
	v_mov_b32_e32 v100, v2
	v_mov_b32_e32 v101, v2
	v_mov_b32_e32 v102, v2
	v_mov_b32_e32 v103, v2
	v_mov_b32_e32 v104, v2
	v_mov_b32_e32 v105, v2
	v_mov_b32_e32 v106, v2
	v_mov_b32_e32 v107, v2
	v_mov_b32_e32 v108, v2
	v_mov_b32_e32 v109, v2
	v_mov_b32_e32 v110, v2
	v_mov_b32_e32 v111, v2
	v_mov_b32_e32 v112, v2
	v_mov_b32_e32 v113, v2
	v_mov_b32_e32 v114, v2
	v_mov_b32_e32 v115, v2
	v_mov_b32_e32 v116, v2
	v_mov_b32_e32 v117, v2
	v_mov_b32_e32 v118, v2
	v_mov_b32_e32 v119, v2
	v_mov_b32_e32 v120, v2
	v_mov_b32_e32 v121, v2
	v_mov_b32_e32 v122, v2
	v_mov_b32_e32 v123, v2
	v_mov_b32_e32 v128, v2
	v_mov_b32_e32 v129, v2
	v_mov_b32_e32 v130, v2
	v_mov_b32_e32 v131, v2
	v_mov_b32_e32 v148, v2
	v_mov_b32_e32 v149, v2
	v_mov_b32_e32 v150, v2
	v_mov_b32_e32 v151, v2
	s_waitcnt lgkmcnt(0)
	s_barrier
	s_cbranch_scc1 .LBB0_199

.LBB0_804:
	s_cmp_lt_i32 s3, 1
	v_lshrrev_b32_e32 v2, 4, v15
	v_bfe_u32 v4, v15, 4, 2
	v_and_b32_e32 v5, 15, v15
	v_bitop3_b32 v8, v2, v5, 3 bitop3:0x6c
	v_or_b32_e32 v2, 4, v4
	v_ashrrev_i32_e32 v7, 1, v15
	v_lshlrev_b32_e32 v9, 8, v2
	v_add_u32_e32 v2, v17, v14
	v_and_b32_e32 v3, 0xc0, v15
	v_lshlrev_b32_e32 v6, 8, v4
	v_and_b32_e32 v7, 0xffffff80, v7
	v_bitop3_b32 v4, v4, v5, 4 bitop3:0x36
	v_add_lshl_u32 v231, v2, v16, 10
	v_mov_b32_e32 v2, 0
	s_mov_b32 s23, 0
	v_lshlrev_b32_e32 v232, 4, v6
	v_lshlrev_b32_e32 v233, 4, v7
	v_lshlrev_b32_e32 v234, 4, v9
	v_lshlrev_b32_e32 v235, 4, v3
	v_lshlrev_b32_e32 v236, 4, v8
	v_lshlrev_b32_e32 v237, 4, v4
	s_mov_b32 s38, 0
	v_mov_b32_e32 v3, v2
	v_mov_b32_e32 v4, v2
	v_mov_b32_e32 v5, v2
	v_mov_b32_e32 v6, v2
	v_mov_b32_e32 v7, v2
	v_mov_b32_e32 v8, v2
	v_mov_b32_e32 v9, v2
	v_mov_b32_e32 v10, v2
	v_mov_b32_e32 v11, v2
	v_mov_b32_e32 v12, v2
	v_mov_b32_e32 v13, v2
	v_mov_b32_e32 v14, v2
	v_mov_b32_e32 v15, v2
	v_mov_b32_e32 v16, v2
	v_mov_b32_e32 v17, v2
	v_mov_b32_e32 v18, v2
	v_mov_b32_e32 v19, v2
	v_mov_b32_e32 v20, v2
	v_mov_b32_e32 v21, v2
	v_mov_b32_e32 v22, v2
	v_mov_b32_e32 v23, v2
	v_mov_b32_e32 v24, v2
	v_mov_b32_e32 v25, v2
	v_mov_b32_e32 v26, v2
	v_mov_b32_e32 v27, v2
	v_mov_b32_e32 v28, v2
	v_mov_b32_e32 v29, v2
	v_mov_b32_e32 v30, v2
	v_mov_b32_e32 v31, v2
	v_mov_b32_e32 v32, v2
	v_mov_b32_e32 v33, v2
	v_mov_b32_e32 v36, v2
	v_mov_b32_e32 v37, v2
	v_mov_b32_e32 v38, v2
	v_mov_b32_e32 v39, v2
	v_mov_b32_e32 v40, v2
	v_mov_b32_e32 v41, v2
	v_mov_b32_e32 v42, v2
	v_mov_b32_e32 v43, v2
	v_mov_b32_e32 v44, v2
	v_mov_b32_e32 v45, v2
	v_mov_b32_e32 v46, v2
	v_mov_b32_e32 v47, v2
	v_mov_b32_e32 v48, v2
	v_mov_b32_e32 v49, v2
	v_mov_b32_e32 v50, v2
	v_mov_b32_e32 v51, v2
	v_mov_b32_e32 v52, v2
	v_mov_b32_e32 v53, v2
	v_mov_b32_e32 v54, v2
	v_mov_b32_e32 v55, v2
	v_mov_b32_e32 v56, v2
	v_mov_b32_e32 v57, v2
	v_mov_b32_e32 v58, v2
	v_mov_b32_e32 v59, v2
	v_mov_b32_e32 v60, v2
	v_mov_b32_e32 v61, v2
	v_mov_b32_e32 v62, v2
	v_mov_b32_e32 v63, v2
	v_mov_b32_e32 v64, v2
	v_mov_b32_e32 v65, v2
	v_mov_b32_e32 v66, v2
	v_mov_b32_e32 v67, v2
	v_mov_b32_e32 v68, v2
	v_mov_b32_e32 v69, v2
	v_mov_b32_e32 v70, v2
	v_mov_b32_e32 v71, v2
	v_mov_b32_e32 v72, v2
	v_mov_b32_e32 v73, v2
	v_mov_b32_e32 v74, v2
	v_mov_b32_e32 v75, v2
	v_mov_b32_e32 v76, v2
	v_mov_b32_e32 v77, v2
	v_mov_b32_e32 v78, v2
	v_mov_b32_e32 v79, v2
	v_mov_b32_e32 v80, v2
	v_mov_b32_e32 v81, v2
	v_mov_b32_e32 v82, v2
	v_mov_b32_e32 v83, v2
	v_mov_b32_e32 v84, v2
	v_mov_b32_e32 v85, v2
	v_mov_b32_e32 v86, v2
	v_mov_b32_e32 v87, v2
	v_mov_b32_e32 v88, v2
	v_mov_b32_e32 v89, v2
	v_mov_b32_e32 v90, v2
	v_mov_b32_e32 v91, v2
	v_mov_b32_e32 v92, v2
	v_mov_b32_e32 v93, v2
	v_mov_b32_e32 v94, v2
	v_mov_b32_e32 v95, v2
	v_mov_b32_e32 v96, v2
	v_mov_b32_e32 v97, v2
	v_mov_b32_e32 v98, v2
	v_mov_b32_e32 v99, v2
	v_mov_b32_e32 v104, v2
	v_mov_b32_e32 v105, v2
	v_mov_b32_e32 v106, v2
	v_mov_b32_e32 v107, v2
	v_mov_b32_e32 v112, v2
	v_mov_b32_e32 v113, v2
	v_mov_b32_e32 v114, v2
	v_mov_b32_e32 v115, v2
	v_mov_b32_e32 v120, v2
	v_mov_b32_e32 v121, v2
	v_mov_b32_e32 v122, v2
	v_mov_b32_e32 v123, v2
	v_mov_b32_e32 v128, v2
	v_mov_b32_e32 v129, v2
	v_mov_b32_e32 v130, v2
	v_mov_b32_e32 v131, v2
	v_mov_b32_e32 v136, v2
	v_mov_b32_e32 v137, v2
	v_mov_b32_e32 v138, v2
	v_mov_b32_e32 v139, v2
	v_mov_b32_e32 v140, v2
	v_mov_b32_e32 v141, v2
	v_mov_b32_e32 v142, v2
	v_mov_b32_e32 v143, v2
	v_mov_b32_e32 v152, v2
	v_mov_b32_e32 v153, v2
	v_mov_b32_e32 v154, v2
	v_mov_b32_e32 v155, v2
	v_mov_b32_e32 v156, v2
	v_mov_b32_e32 v157, v2
	v_mov_b32_e32 v158, v2
	v_mov_b32_e32 v159, v2
	s_waitcnt lgkmcnt(0)
	s_barrier
	s_cbranch_scc1 .LBB0_811
